# v54 + loop-invariant ones-fragment SGPR setup hoisted out of the attention far blocks (3 fewer SALU per far half-block)
# baseline (speedup 1.0000x reference)
.LBB0_134:
	s_mov_b32 s65, s64
	s_mov_b32 s66, s64
	s_mov_b32 s67, s64
	s_and_b32 s11, s40, 7
	s_and_saveexec_b64 s[6:7], s[42:43]
	s_cbranch_execz .LBB0_136
	s_mul_i32 s8, s11, 0x84
	v_add_u32_e32 v2, s8, v133
	v_ashrrev_i32_e32 v3, 31, v2
	v_lshl_add_u64 v[2:3], v[2:3], 2, s[2:3]
	global_load_dword v0, v[2:3], off
	s_waitcnt vmcnt(0)
	ds_write_b32 v194, v0

.Lfar_a2:
	s_lshl_b32 s13, s29, 6
	s_mul_i32 s12, s29, 0x2200
	v_add_u32_e32 v171, s12, v139
	ds_read_b128 v[222:225], v171 offset:1024
	ds_read_b128 v[226:229], v171 offset:1088
	ds_read_b128 v[230:233], v171 offset:2112
	ds_read_b128 v[234:237], v171 offset:2176
	s_waitcnt lgkmcnt(3)
	v_mfma_f32_16x16x32_bf16 v[222:225], v[222:225], v[4:7], v[252:255]
	s_waitcnt lgkmcnt(1)
	v_mfma_f32_16x16x32_bf16 v[230:233], v[230:233], v[4:7], v[252:255]
	v_mfma_f32_16x16x32_bf16 v[222:225], v[226:229], v[8:11], v[222:225]
	ds_read_b128 v[226:229], v171 offset:1152
	ds_read_b128 v[238:241], v171 offset:1216
	s_waitcnt lgkmcnt(2)
	v_mfma_f32_16x16x32_bf16 v[230:233], v[234:237], v[8:11], v[230:233]
	ds_read_b128 v[234:237], v171 offset:2240
	ds_read_b128 v[242:245], v171 offset:2304
	s_nop 2
	v_exp_f32_e32 v3, v223
	v_exp_f32_e32 v219, v225
	s_waitcnt lgkmcnt(3)
	v_mfma_f32_16x16x32_bf16 v[226:229], v[226:229], v[12:15], v[252:255]
	v_exp_f32_e32 v225, v231
	s_waitcnt lgkmcnt(2)
	v_mfma_f32_16x16x32_bf16 v[226:229], v[238:241], v[16:19], v[226:229]
	v_add3_u32 v0, s13, v134, v135
	v_exp_f32_e32 v217, v224
	s_waitcnt lgkmcnt(1)
	v_mfma_f32_16x16x32_bf16 v[172:175], v[234:237], v[12:15], v[252:255]
	ds_read_b128 v[234:237], v0 offset:18432
	ds_read_b128 v[238:241], v0 offset:20736
	s_nop 1
	v_exp_f32_e32 v2, v226
	v_exp_f32_e32 v171, v227
	s_waitcnt lgkmcnt(2)
	v_mfma_f32_16x16x32_bf16 v[172:175], v[242:245], v[16:19], v[172:175]
	ds_read_b128 v[242:245], v0 offset:23040
	ds_read_b128 v[246:249], v0 offset:25344
	v_exp_f32_e32 v0, v222
	v_exp_f32_e32 v218, v228
	v_exp_f32_e32 v223, v229
	v_exp_f32_e32 v222, v230
	s_nop 1
	v_exp_f32_e32 v224, v172
	v_exp_f32_e32 v226, v173
	v_exp_f32_e32 v227, v232
	v_exp_f32_e32 v228, v174
	v_exp_f32_e32 v229, v233
	v_exp_f32_e32 v230, v175
	v_cvt_pk_bf16_f32 v172, v0, v3
	v_cvt_pk_bf16_f32 v173, v217, v219
	v_cvt_pk_bf16_f32 v174, v222, v225
	v_cvt_pk_bf16_f32 v175, v227, v229
	v_cvt_pk_bf16_f32 v222, v2, v171
	v_cvt_pk_bf16_f32 v223, v218, v223
	v_cvt_pk_bf16_f32 v224, v224, v226
	v_cvt_pk_bf16_f32 v225, v228, v230
	v_add3_u32 v0, s13, v135, v134
	s_waitcnt lgkmcnt(3)
	v_mfma_f32_16x16x32_bf16 v[104:107], v[234:237], v[172:175], v[104:107]
	ds_read_b128 v[226:229], v0 offset:27648
	ds_read_b128 v[230:233], v0 offset:29952
	v_mfma_f32_16x16x32_bf16 v[112:115], v[234:237], v[222:225], v[112:115]
	ds_read_b128 v[234:237], v0 offset:32256
	s_waitcnt lgkmcnt(5)
	v_mfma_f32_16x16x32_bf16 v[100:103], v[238:241], v[172:175], v[100:103]
	v_mfma_f32_16x16x32_bf16 v[108:111], v[238:241], v[222:225], v[108:111]
	ds_read_b128 v[238:241], v0 offset:34560
	s_waitcnt lgkmcnt(5)
	v_mfma_f32_16x16x32_bf16 v[88:91], v[242:245], v[172:175], v[88:91]
	v_mfma_f32_16x16x32_bf16 v[96:99], v[242:245], v[222:225], v[96:99]
	v_mfma_f32_16x16x32_bf16 v[84:87], v[246:249], v[172:175], v[84:87]
	v_mfma_f32_16x16x32_bf16 v[92:95], v[246:249], v[222:225], v[92:95]
	s_waitcnt lgkmcnt(3)
	v_mfma_f32_16x16x32_bf16 v[72:75], v[226:229], v[172:175], v[72:75]
	v_mfma_f32_16x16x32_bf16 v[80:83], v[226:229], v[222:225], v[80:83]
	v_mov_b64_e32 v[228:229], s[66:67]
	v_mov_b64_e32 v[226:227], s[64:65]
	s_waitcnt lgkmcnt(2)
	v_mfma_f32_16x16x32_bf16 v[68:71], v[230:233], v[172:175], v[68:71]
	v_mfma_f32_16x16x32_bf16 v[76:79], v[230:233], v[222:225], v[76:79]
	s_waitcnt lgkmcnt(1)
	v_mfma_f32_16x16x32_bf16 v[56:59], v[234:237], v[172:175], v[56:59]
	v_mfma_f32_16x16x32_bf16 v[64:67], v[234:237], v[222:225], v[64:67]
	s_waitcnt lgkmcnt(0)
	v_mfma_f32_16x16x32_bf16 v[52:55], v[238:241], v[172:175], v[52:55]
	v_mfma_f32_16x16x32_bf16 v[60:63], v[238:241], v[222:225], v[60:63]
	v_mfma_f32_16x16x32_bf16 v[128:131], v[226:229], v[172:175], v[128:131]
	v_mfma_f32_16x16x32_bf16 v[116:119], v[226:229], v[222:225], v[116:119]
	s_branch .LBB0_142

.Lfar_b2:
	s_lshl_b32 s13, s29, 6
	s_mul_i32 s12, s29, 0x2200
	v_add_u32_e32 v171, s12, v139
	ds_read_b128 v[222:225], v171 offset:36864
	ds_read_b128 v[226:229], v171 offset:36928
	ds_read_b128 v[230:233], v171 offset:37952
	ds_read_b128 v[234:237], v171 offset:38016
	s_waitcnt lgkmcnt(3)
	v_mfma_f32_16x16x32_bf16 v[222:225], v[222:225], v[4:7], v[252:255]
	s_waitcnt lgkmcnt(1)
	v_mfma_f32_16x16x32_bf16 v[230:233], v[230:233], v[4:7], v[252:255]
	v_mfma_f32_16x16x32_bf16 v[222:225], v[226:229], v[8:11], v[222:225]
	ds_read_b128 v[226:229], v171 offset:36992
	ds_read_b128 v[238:241], v171 offset:37056
	s_waitcnt lgkmcnt(2)
	v_mfma_f32_16x16x32_bf16 v[230:233], v[234:237], v[8:11], v[230:233]
	ds_read_b128 v[234:237], v171 offset:38080
	ds_read_b128 v[242:245], v171 offset:38144
	s_nop 2
	v_exp_f32_e32 v3, v223
	v_exp_f32_e32 v219, v225
	s_waitcnt lgkmcnt(3)
	v_mfma_f32_16x16x32_bf16 v[226:229], v[226:229], v[12:15], v[252:255]
	v_exp_f32_e32 v225, v231
	s_waitcnt lgkmcnt(2)
	v_mfma_f32_16x16x32_bf16 v[226:229], v[238:241], v[16:19], v[226:229]
	v_add3_u32 v0, s13, v134, v135
	v_exp_f32_e32 v217, v224
	s_waitcnt lgkmcnt(1)
	v_mfma_f32_16x16x32_bf16 v[172:175], v[234:237], v[12:15], v[252:255]
	ds_read_b128 v[234:237], v0 offset:54272
	ds_read_b128 v[238:241], v0 offset:56576
	s_nop 1
	v_exp_f32_e32 v2, v226
	v_exp_f32_e32 v171, v227
	s_waitcnt lgkmcnt(2)
	v_mfma_f32_16x16x32_bf16 v[172:175], v[242:245], v[16:19], v[172:175]
	ds_read_b128 v[242:245], v0 offset:58880
	ds_read_b128 v[246:249], v0 offset:61184
	v_exp_f32_e32 v0, v222
	v_exp_f32_e32 v218, v228
	v_exp_f32_e32 v223, v229
	v_exp_f32_e32 v222, v230
	s_nop 1
	v_exp_f32_e32 v224, v172
	v_exp_f32_e32 v226, v173
	v_exp_f32_e32 v227, v232
	v_exp_f32_e32 v228, v174
	v_exp_f32_e32 v229, v233
	v_exp_f32_e32 v230, v175
	v_cvt_pk_bf16_f32 v172, v0, v3
	v_cvt_pk_bf16_f32 v173, v217, v219
	v_cvt_pk_bf16_f32 v174, v222, v225
	v_cvt_pk_bf16_f32 v175, v227, v229
	v_cvt_pk_bf16_f32 v222, v2, v171
	v_cvt_pk_bf16_f32 v223, v218, v223
	v_cvt_pk_bf16_f32 v224, v224, v226
	v_cvt_pk_bf16_f32 v225, v228, v230
	v_add3_u32 v0, s13, v135, v134
	v_add_u32_e32 v2, 0x10100, v0
	ds_read_b128 v[226:229], v0 offset:63488
	ds_read_b128 v[230:233], v2
	v_add_u32_e32 v2, 0x10a00, v0
	v_add_u32_e32 v0, 0x11300, v0
	s_waitcnt lgkmcnt(5)
	v_mfma_f32_16x16x32_bf16 v[104:107], v[234:237], v[172:175], v[104:107]
	v_mfma_f32_16x16x32_bf16 v[112:115], v[234:237], v[222:225], v[112:115]
	ds_read_b128 v[234:237], v2
	s_waitcnt lgkmcnt(5)
	v_mfma_f32_16x16x32_bf16 v[100:103], v[238:241], v[172:175], v[100:103]
	v_mfma_f32_16x16x32_bf16 v[108:111], v[238:241], v[222:225], v[108:111]
	ds_read_b128 v[238:241], v0
	s_waitcnt lgkmcnt(5)
	v_mfma_f32_16x16x32_bf16 v[88:91], v[242:245], v[172:175], v[88:91]
	v_mfma_f32_16x16x32_bf16 v[96:99], v[242:245], v[222:225], v[96:99]
	v_mfma_f32_16x16x32_bf16 v[84:87], v[246:249], v[172:175], v[84:87]
	v_mfma_f32_16x16x32_bf16 v[92:95], v[246:249], v[222:225], v[92:95]
	s_waitcnt lgkmcnt(3)
	v_mfma_f32_16x16x32_bf16 v[72:75], v[226:229], v[172:175], v[72:75]
	v_mfma_f32_16x16x32_bf16 v[80:83], v[226:229], v[222:225], v[80:83]
	v_mov_b64_e32 v[228:229], s[66:67]
	v_mov_b64_e32 v[226:227], s[64:65]
	s_waitcnt lgkmcnt(2)
	v_mfma_f32_16x16x32_bf16 v[68:71], v[230:233], v[172:175], v[68:71]
	v_mfma_f32_16x16x32_bf16 v[76:79], v[230:233], v[222:225], v[76:79]
	s_waitcnt lgkmcnt(1)
	v_mfma_f32_16x16x32_bf16 v[56:59], v[234:237], v[172:175], v[56:59]
	v_mfma_f32_16x16x32_bf16 v[64:67], v[234:237], v[222:225], v[64:67]
	s_waitcnt lgkmcnt(0)
	v_mfma_f32_16x16x32_bf16 v[52:55], v[238:241], v[172:175], v[52:55]
	v_mfma_f32_16x16x32_bf16 v[60:63], v[238:241], v[222:225], v[60:63]
	v_mfma_f32_16x16x32_bf16 v[128:131], v[226:229], v[172:175], v[128:131]
	v_mfma_f32_16x16x32_bf16 v[116:119], v[226:229], v[222:225], v[116:119]
	s_branch .LBB0_168
